# unpack v_pk rescale ops in fox/DSA online-softmax blocks into plain f32 ops
# speedup vs baseline: 1.0017x; 1.0017x over previous
.LBB0_830:
	v_add_f32_e32 v112, v112, v106
	v_sub_f32_e32 v34, v34, v106
	v_sub_f32_e32 v35, v35, v106
	v_sub_f32_e32 v50, v50, v106
	v_sub_f32_e32 v51, v51, v106
	v_sub_f32_e32 v36, v36, v106
	v_sub_f32_e32 v37, v37, v106
	v_sub_f32_e32 v52, v52, v106
	v_sub_f32_e32 v53, v53, v106
	v_sub_f32_e32 v38, v38, v106
	v_sub_f32_e32 v39, v39, v106
	v_sub_f32_e32 v54, v54, v106
	v_sub_f32_e32 v55, v55, v106
	v_sub_f32_e32 v40, v40, v106
	v_sub_f32_e32 v41, v41, v106
	v_sub_f32_e32 v56, v56, v106
	v_sub_f32_e32 v57, v57, v106
	v_sub_f32_e32 v42, v42, v106
	v_sub_f32_e32 v43, v43, v106
	v_sub_f32_e32 v58, v58, v106
	v_sub_f32_e32 v59, v59, v106
	v_sub_f32_e32 v44, v44, v106
	v_sub_f32_e32 v45, v45, v106
	v_sub_f32_e32 v60, v60, v106
	v_sub_f32_e32 v61, v61, v106
	v_sub_f32_e32 v46, v46, v106
	v_sub_f32_e32 v47, v47, v106
	v_sub_f32_e32 v62, v62, v106
	v_sub_f32_e32 v63, v63, v106
	v_sub_f32_e32 v48, v48, v106
	v_sub_f32_e32 v49, v49, v106
	v_sub_f32_e32 v64, v64, v106
	v_sub_f32_e32 v65, v65, v106
	v_mul_f32_e32 v32, v32, v104
	v_mul_f32_e32 v33, v33, v104
	v_mul_f32_e32 v30, v30, v104
	v_mul_f32_e32 v31, v31, v104
	v_mul_f32_e32 v28, v28, v104
	v_mul_f32_e32 v29, v29, v104
	v_mul_f32_e32 v26, v26, v104
	v_mul_f32_e32 v27, v27, v104
	v_mul_f32_e32 v24, v24, v104
	v_mul_f32_e32 v25, v25, v104
	v_mul_f32_e32 v22, v22, v104
	v_mul_f32_e32 v23, v23, v104
	v_mul_f32_e32 v20, v20, v104
	v_mul_f32_e32 v21, v21, v104
	v_mul_f32_e32 v18, v18, v104
	v_mul_f32_e32 v19, v19, v104
	v_mul_f32_e32 v16, v16, v104
	v_mul_f32_e32 v17, v17, v104
	v_mul_f32_e32 v14, v14, v104
	v_mul_f32_e32 v15, v15, v104
	v_mul_f32_e32 v12, v12, v104
	v_mul_f32_e32 v13, v13, v104
	v_mul_f32_e32 v10, v10, v104
	v_mul_f32_e32 v11, v11, v104
	v_mul_f32_e32 v8, v8, v104
	v_mul_f32_e32 v9, v9, v104
	v_mul_f32_e32 v6, v6, v104
	v_mul_f32_e32 v7, v7, v104
	v_mul_f32_e32 v4, v4, v104
	v_mul_f32_e32 v5, v5, v104
	v_mul_f32_e32 v2, v2, v104
	v_mul_f32_e32 v3, v3, v104
	v_mul_f32_e32 v114, v114, v104

.LBB0_924:
	v_add_f32_e32 v112, v112, v110
	v_sub_f32_e32 v34, v34, v110
	v_sub_f32_e32 v35, v35, v110
	v_sub_f32_e32 v50, v50, v110
	v_sub_f32_e32 v51, v51, v110
	v_sub_f32_e32 v36, v36, v110
	v_sub_f32_e32 v37, v37, v110
	v_sub_f32_e32 v52, v52, v110
	v_sub_f32_e32 v53, v53, v110
	v_sub_f32_e32 v38, v38, v110
	v_sub_f32_e32 v39, v39, v110
	v_sub_f32_e32 v54, v54, v110
	v_sub_f32_e32 v55, v55, v110
	v_sub_f32_e32 v40, v40, v110
	v_sub_f32_e32 v41, v41, v110
	v_sub_f32_e32 v56, v56, v110
	v_sub_f32_e32 v57, v57, v110
	v_sub_f32_e32 v42, v42, v110
	v_sub_f32_e32 v43, v43, v110
	v_sub_f32_e32 v58, v58, v110
	v_sub_f32_e32 v59, v59, v110
	v_sub_f32_e32 v44, v44, v110
	v_sub_f32_e32 v45, v45, v110
	v_sub_f32_e32 v60, v60, v110
	v_sub_f32_e32 v61, v61, v110
	v_sub_f32_e32 v46, v46, v110
	v_sub_f32_e32 v47, v47, v110
	v_sub_f32_e32 v62, v62, v110
	v_sub_f32_e32 v63, v63, v110
	v_sub_f32_e32 v48, v48, v110
	v_sub_f32_e32 v49, v49, v110
	v_sub_f32_e32 v64, v64, v110
	v_sub_f32_e32 v65, v65, v110
	v_mul_f32_e32 v32, v32, v108
	v_mul_f32_e32 v33, v33, v108
	v_mul_f32_e32 v30, v30, v108
	v_mul_f32_e32 v31, v31, v108
	v_mul_f32_e32 v28, v28, v108
	v_mul_f32_e32 v29, v29, v108
	v_mul_f32_e32 v26, v26, v108
	v_mul_f32_e32 v27, v27, v108
	v_mul_f32_e32 v24, v24, v108
	v_mul_f32_e32 v25, v25, v108
	v_mul_f32_e32 v22, v22, v108
	v_mul_f32_e32 v23, v23, v108
	v_mul_f32_e32 v20, v20, v108
	v_mul_f32_e32 v21, v21, v108
	v_mul_f32_e32 v18, v18, v108
	v_mul_f32_e32 v19, v19, v108
	v_mul_f32_e32 v16, v16, v108
	v_mul_f32_e32 v17, v17, v108
	v_mul_f32_e32 v14, v14, v108
	v_mul_f32_e32 v15, v15, v108
	v_mul_f32_e32 v12, v12, v108
	v_mul_f32_e32 v13, v13, v108
	v_mul_f32_e32 v10, v10, v108
	v_mul_f32_e32 v11, v11, v108
	v_mul_f32_e32 v8, v8, v108
	v_mul_f32_e32 v9, v9, v108
	v_mul_f32_e32 v6, v6, v108
	v_mul_f32_e32 v7, v7, v108
	v_mul_f32_e32 v4, v4, v108
	v_mul_f32_e32 v5, v5, v108
	v_mul_f32_e32 v2, v2, v108
	v_mul_f32_e32 v3, v3, v108
	v_mul_f32_e32 v111, v111, v108
